# O1 and E1a wide-tile phases both staggered by ~12us for the second co-resident workgroup
# baseline (speedup 1.0000x reference)
;   DI u16* xb() const { return (u16*)(ws + WS_xb); }
;   DI u16* Wt_in_e() const { return (u16*)(ws + WS_Wt_in_e); }
; DI TileSched tile_sched(int ntot) {
;   TileSched ts;
;   if ((gridDim.x & 7) == 0) {
;     const int xcd = blockIdx.x & 7, j = blockIdx.x >> 3, nb = gridDim.x >> 3;
;     ts.t = (int)(((long)ntot * xcd) >> 3) + j; ts.hi = (int)(((long)ntot * (xcd + 1)) >> 3); ts.step = nb;
;   } else { ts.t = blockIdx.x; ts.hi = ntot; ts.step = gridDim.x; }
;   return ts;
; }
; __global__ void __launch_bounds__(256, 2) fwd_megakernel(Params p) {
;     ...
;   for (TileSched ts = tile_sched(128 * 12); ts.t < ts.hi; ts.t += ts.step) {
;     const int mt = ts.t / 12, n2 = ts.t % 12;
;     gemm_tile_wide<1024>(p.xb(), 1024, p.Wt_in_e(), 1024, mt * 128, n2 * 256, smem, [&](int half) { epi_e1a(p, mt, 2 * n2 + half, (const float*)smem); });
.LBB0_138:
	v_writelane_b32 v247, s90, 28
	s_cmp_ge_i32 s88, s50
	v_mbcnt_lo_u32_b32 v187, -1, 0
	v_writelane_b32 v247, s91, 29
	s_cbranch_scc1 .LBB0_231
	s_getreg_b32 s99, hwreg(HW_REG_LDS_ALLOC, 0, 12)
	s_cmp_eq_u32 s99, 0
	s_cbranch_scc1 .Lstag_e1a
	s_sleep 127
	s_sleep 127
	s_sleep 127
.Lstag_e1a:
	s_add_u32 s0, s86, 0x8000
	s_addc_u32 s1, s87, 0
	v_writelane_b32 v247, s0, 30
	v_mov_b32_e32 v137, 0
	s_movk_i32 s16, 0x4000
	v_writelane_b32 v247, s1, 31
	s_add_u32 s0, s86, 0x2108000
	s_addc_u32 s1, s87, 0
	v_writelane_b32 v247, s0, 32
	s_mov_b32 s97, 0
	s_movk_i32 s17, 0x210
	v_writelane_b32 v247, s1, 33
	s_add_u32 s0, s84, 0x6c00000
	s_addc_u32 s1, s85, 0
	s_add_u32 s26, s84, 0x10d50000
	s_addc_u32 s27, s85, 0
	s_add_u32 s28, s86, 0x72b0000
	s_addc_u32 s29, s87, 0
	s_add_u32 s30, s86, 0x20711000
	s_addc_u32 s31, s87, 0
	s_add_u32 s38, s86, 0x20771000
	s_addc_u32 s39, s87, 0
	s_add_u32 s44, s84, 0x4c00000
	s_addc_u32 s45, s85, 0
	s_add_u32 s46, s84, 0x10c50000
	s_addc_u32 s47, s85, 0
	s_add_u32 s68, s86, 0x6230000
	s_addc_u32 s69, s87, 0
	s_add_u32 s70, s86, 0x51b0000
	s_addc_u32 s71, s87, 0
	s_add_u32 s72, s84, 0x4200000
	s_addc_u32 s73, s85, 0
	s_add_u32 s76, s84, 0x10c00000
	s_addc_u32 s77, s85, 0
	s_add_u32 s78, s86, 0x3c08000
	s_addc_u32 s79, s87, 0
	s_add_u32 s89, s86, 0x33c8000
	s_addc_u32 s33, s87, 0
	s_add_u32 s80, s86, 0x182f0000
	s_addc_u32 s81, s87, 0
	s_add_u32 s82, s84, 0x4a00000
	s_addc_u32 s83, s85, 0
	s_add_u32 s90, s84, 0x10c40000
	s_addc_u32 s91, s85, 0
	s_add_u32 s92, s86, 0x8040
	s_addc_u32 s93, s87, 0
	s_add_u32 s94, s86, 0x2108040
	v_writelane_b32 v247, s0, 34
	s_addc_u32 s95, s87, 0
	s_movk_i32 s51, 0x3fff
	v_mov_b32_e32 v164, 0x3727c5ac
	s_movk_i32 s20, 0x140
	v_mov_b32_e32 v165, 0x800
	v_mbcnt_hi_u32_b32 v166, -1, v187
	v_writelane_b32 v247, s1, 35
	s_branch .LBB0_141
